# row_post work queue (after the z GEMM) also takes the most recently written 2048-row chunks first
# baseline (speedup 1.0000x reference)
; #define INP(i) ((const float*)tab_get(lds, (i)))
; #define OUTP() ((float*)tab_get(lds, 30))
; #define WSB(off) ((bf16*)((unsigned char*)tab_get(lds, 31) + (off)))
; #define fresh_lane() (my_tid(lds) & 63)
; #define QNEXT(ctrw, dst) do { __syncthreads(); if (my_tid(lds) == 0) *(volatile LAS int*)(lds + TAB_OFF + 264) = (int)atomicAdd((unsigned*)tab_get(lds, 31) + 8192 + 64 * (ctrw), 1u); \
;         __syncthreads(); dst = __builtin_amdgcn_readfirstlane(*(volatile LAS int*)(lds + TAB_OFF + 264)); } while (0)
; __global__ void __launch_bounds__(512, 2) mega_fwd(Params p) {
;     ...
;         { const int lane = fresh_lane(); bf16 *Z = WSB(WS_Z), *CQN = WSB(WS_CQN), *CKV = WSB(WS_CKV), *KR = WSB(WS_KR); float* out = OUTP(); const float *qg = INP(11), *kvg = INP(12);
;           for (;;) { int it; QNEXT(0, it); if (it >= MP / 64) break;
; #pragma unroll 1
;               for (int k = 0; k < 8; ++k) row_post(Z, CQN, CKV, KR, out, qg, kvg, it * 64 + wave * 8 + k, lane); } }
.LBB0_318:
	s_or_b64 exec, exec, s[8:9]
	s_waitcnt lgkmcnt(0)
	s_barrier
	ds_read_b32 v20, v38
	s_mov_b64 s[8:9], -1
	s_waitcnt lgkmcnt(0)
	v_readfirstlane_b32 s4, v20
	s_cmpk_gt_i32 s4, 0x1ff
	s_cbranch_scc1 .LBB0_315
	s_lshr_b32 s8, s4, 5
	s_and_b32 s9, s4, 31
	s_lshl_b32 s4, s8, 1
	s_or_b32 s4, s4, 1
	s_cmp_lt_u32 s8, 8
	s_cselect_b32 s8, 0, 17
	s_sub_i32 s4, s4, s8
	s_lshl_b32 s4, s4, 5
	s_or_b32 s4, s4, s9
	s_lshl_b32 s4, s4, 6
	s_add_i32 s8, s4, s70
	s_ashr_i32 s9, s8, 31
	s_lshl_b64 s[10:11], s[8:9], 8
	v_lshl_add_u64 v[20:21], v[6:7], 0, s[10:11]
	s_lshl_b64 s[10:11], s[8:9], 6
	v_lshl_add_u64 v[22:23], v[8:9], 0, s[10:11]
	s_lshl_b64 s[10:11], s[8:9], 9
	s_add_u32 s28, s20, s10
	v_lshl_add_u64 v[24:25], v[10:11], 0, s[10:11]
	s_addc_u32 s29, s21, s11
	v_mad_i64_i32 v[26:27], s[10:11], s8, v40, v[12:13]
	v_mad_i64_i32 v[28:29], s[10:11], s8, v40, v[14:15]
	v_mad_i64_i32 v[30:31], s[10:11], s8, v40, v[16:17]
	s_add_i32 s4, s23, s4
	s_and_b32 s30, s8, 0x3fff
	s_lshl_b64 s[10:11], s[4:5], 9
	s_add_u32 s31, s24, s10
	s_addc_u32 s34, s25, s11
	s_mov_b64 s[10:11], 0
	s_mov_b64 s[12:13], 0
	s_mov_b64 s[14:15], 0
	s_branch .LBB0_321
